# v017 + B-fragment reads of the FFN-up/down main loops from one base VGPR with immediate offsets (3 fewer VALU adds per iteration in load segments)
# speedup vs baseline: 1.0058x; 1.0058x over previous
.Lsp_LBB0269:
	v_add_u32_e32 v143, 0x10000, v140
	ds_read_b128 v[136:139], v143
	ds_read_b128 v[144:147], v143 offset:1024
	ds_read_b128 v[148:151], v143 offset:2048
	ds_read_b128 v[152:155], v143 offset:3072
	ds_read_b128 v[168:171], v143 offset:16384
	ds_read_b128 v[172:175], v143 offset:17408
	ds_read_b128 v[176:179], v143 offset:18432
	ds_read_b128 v[180:183], v143 offset:19456
	ds_read_b128 v[184:187], v142
	ds_read_b128 v[188:191], v142 offset:1024
	ds_read_b128 v[192:195], v142 offset:2048
	ds_read_b128 v[196:199], v142 offset:3072
	ds_read_b128 v[200:203], v142 offset:4096
	ds_read_b128 v[204:207], v142 offset:5120
	ds_read_b128 v[216:219], v142 offset:6144
	ds_read_b128 v[220:223], v142 offset:7168
	s_or_b32 s54, s35, 1
	s_lshl_b64 s[16:17], s[54:55], 7
	s_add_i32 s54, s35, 2
	s_lshl_b64 s[44:45], s[54:55], 7
	s_add_u32 s46, s66, s44
	s_addc_u32 s47, s67, s45
	s_and_b64 vcc, s[14:15], exec
	s_cselect_b32 vcc_hi, s29, s47
	s_cselect_b32 vcc_lo, s65, s46
	s_add_u32 s44, s70, s44
	s_addc_u32 s45, s71, s45
	s_and_b64 s[14:15], s[14:15], exec
	s_cselect_b32 s15, s51, s45
	s_cselect_b32 s14, s30, s44
	s_add_i32 s44, 0, 0x10000
	s_add_i32 s45, 0, 0x14000
	s_add_i32 m0, s73, 0xc000
	s_add_u32 s16, s31, s16
	s_addc_u32 s17, s34, s17
	global_load_lds_dwordx4 v130, s[16:17]
	s_add_i32 m0, s73, 0xe000
	s_nop 0
	global_load_lds_dwordx4 v132, s[16:17]
	s_waitcnt vmcnt(8)
	s_waitcnt lgkmcnt(0)
	s_barrier
	s_waitcnt lgkmcnt(0)
	v_mfma_f32_16x16x32_bf16 v[122:125], v[136:139], v[184:187], v[122:125]
	v_mfma_f32_16x16x32_bf16 v[122:125], v[144:147], v[188:191], v[122:125]
	v_mfma_f32_16x16x32_bf16 v[114:117], v[148:151], v[184:187], v[114:117]
	v_mfma_f32_16x16x32_bf16 v[114:117], v[152:155], v[188:191], v[114:117]
	v_mfma_f32_16x16x32_bf16 v[106:109], v[136:139], v[192:195], v[106:109]
	v_mfma_f32_16x16x32_bf16 v[106:109], v[144:147], v[196:199], v[106:109]
	v_mfma_f32_16x16x32_bf16 v[102:105], v[148:151], v[192:195], v[102:105]
	v_mfma_f32_16x16x32_bf16 v[102:105], v[152:155], v[196:199], v[102:105]
	v_mfma_f32_16x16x32_bf16 v[90:93], v[136:139], v[200:203], v[90:93]
	v_mfma_f32_16x16x32_bf16 v[90:93], v[144:147], v[204:207], v[90:93]
	v_mfma_f32_16x16x32_bf16 v[86:89], v[148:151], v[200:203], v[86:89]
	v_mfma_f32_16x16x32_bf16 v[86:89], v[152:155], v[204:207], v[86:89]
	v_mfma_f32_16x16x32_bf16 v[74:77], v[136:139], v[216:219], v[74:77]
	v_mfma_f32_16x16x32_bf16 v[74:77], v[144:147], v[220:223], v[74:77]
	v_mfma_f32_16x16x32_bf16 v[70:73], v[148:151], v[216:219], v[70:73]
	v_mfma_f32_16x16x32_bf16 v[70:73], v[152:155], v[220:223], v[70:73]
	v_mfma_f32_16x16x32_bf16 v[126:129], v[168:171], v[184:187], v[126:129]
	v_mfma_f32_16x16x32_bf16 v[126:129], v[172:175], v[188:191], v[126:129]
	v_mfma_f32_16x16x32_bf16 v[118:121], v[176:179], v[184:187], v[118:121]
	v_mfma_f32_16x16x32_bf16 v[118:121], v[180:183], v[188:191], v[118:121]
	v_mfma_f32_16x16x32_bf16 v[110:113], v[168:171], v[192:195], v[110:113]
	v_mfma_f32_16x16x32_bf16 v[110:113], v[172:175], v[196:199], v[110:113]
	v_mfma_f32_16x16x32_bf16 v[98:101], v[176:179], v[192:195], v[98:101]
	v_mfma_f32_16x16x32_bf16 v[98:101], v[180:183], v[196:199], v[98:101]
	v_mfma_f32_16x16x32_bf16 v[94:97], v[168:171], v[200:203], v[94:97]
	v_mfma_f32_16x16x32_bf16 v[94:97], v[172:175], v[204:207], v[94:97]
	v_mfma_f32_16x16x32_bf16 v[82:85], v[176:179], v[200:203], v[82:85]
	v_mfma_f32_16x16x32_bf16 v[82:85], v[180:183], v[204:207], v[82:85]
	v_mfma_f32_16x16x32_bf16 v[78:81], v[168:171], v[216:219], v[78:81]
	v_mfma_f32_16x16x32_bf16 v[78:81], v[172:175], v[220:223], v[78:81]
	v_mfma_f32_16x16x32_bf16 v[66:69], v[176:179], v[216:219], v[66:69]
	v_mfma_f32_16x16x32_bf16 v[66:69], v[180:183], v[220:223], v[66:69]
	s_barrier
	s_add_i32 s16, s44, s61
	s_mov_b32 m0, s16
	ds_read_b128 v[184:187], v142 offset:16384
	ds_read_b128 v[188:191], v142 offset:17408
	ds_read_b128 v[192:195], v142 offset:18432
	ds_read_b128 v[196:199], v142 offset:19456
	ds_read_b128 v[200:203], v142 offset:20480
	ds_read_b128 v[204:207], v142 offset:21504
	ds_read_b128 v[216:219], v142 offset:22528
	ds_read_b128 v[220:223], v142 offset:23552
	global_load_lds_dwordx4 v158, s[14:15]
	s_add_i32 m0, s16, 0x2000
	s_nop 0
	global_load_lds_dwordx4 v134, s[14:15]
	s_add_u32 s16, s14, 0x80000
	s_addc_u32 s17, s15, 0
	s_add_i32 s44, s45, s61
	s_mov_b32 m0, s44
	s_nop 0
	global_load_lds_dwordx4 v158, s[16:17]
	s_add_i32 m0, s44, 0x2000
	s_nop 0
	global_load_lds_dwordx4 v134, s[16:17]
	s_mov_b32 m0, s73
	s_nop 0
	global_load_lds_dwordx4 v130, vcc
	s_mov_b32 m0, s75
	s_nop 0
	global_load_lds_dwordx4 v132, vcc
	s_waitcnt vmcnt(8)
	s_waitcnt lgkmcnt(0)
	s_barrier
	s_waitcnt lgkmcnt(0)
	v_mfma_f32_16x16x32_bf16 v[58:61], v[136:139], v[184:187], v[58:61]
	v_mfma_f32_16x16x32_bf16 v[58:61], v[144:147], v[188:191], v[58:61]
	v_mfma_f32_16x16x32_bf16 v[54:57], v[148:151], v[184:187], v[54:57]
	v_mfma_f32_16x16x32_bf16 v[54:57], v[152:155], v[188:191], v[54:57]
	v_mfma_f32_16x16x32_bf16 v[42:45], v[136:139], v[192:195], v[42:45]
	v_mfma_f32_16x16x32_bf16 v[42:45], v[144:147], v[196:199], v[42:45]
	v_mfma_f32_16x16x32_bf16 v[38:41], v[148:151], v[192:195], v[38:41]
	v_mfma_f32_16x16x32_bf16 v[38:41], v[152:155], v[196:199], v[38:41]
	v_mfma_f32_16x16x32_bf16 v[26:29], v[136:139], v[200:203], v[26:29]
	v_mfma_f32_16x16x32_bf16 v[26:29], v[144:147], v[204:207], v[26:29]
	v_mfma_f32_16x16x32_bf16 v[22:25], v[148:151], v[200:203], v[22:25]
	v_mfma_f32_16x16x32_bf16 v[22:25], v[152:155], v[204:207], v[22:25]
	v_mfma_f32_16x16x32_bf16 v[10:13], v[136:139], v[216:219], v[10:13]
	v_mfma_f32_16x16x32_bf16 v[10:13], v[144:147], v[220:223], v[10:13]
	v_mfma_f32_16x16x32_bf16 v[2:5], v[148:151], v[216:219], v[2:5]
	v_mfma_f32_16x16x32_bf16 v[2:5], v[152:155], v[220:223], v[2:5]
	v_mfma_f32_16x16x32_bf16 v[62:65], v[168:171], v[184:187], v[62:65]
	v_mfma_f32_16x16x32_bf16 v[62:65], v[172:175], v[188:191], v[62:65]
	v_mfma_f32_16x16x32_bf16 v[50:53], v[176:179], v[184:187], v[50:53]
	v_mfma_f32_16x16x32_bf16 v[50:53], v[180:183], v[188:191], v[50:53]
	v_mfma_f32_16x16x32_bf16 v[46:49], v[168:171], v[192:195], v[46:49]
	v_mfma_f32_16x16x32_bf16 v[46:49], v[172:175], v[196:199], v[46:49]
	v_mfma_f32_16x16x32_bf16 v[34:37], v[176:179], v[192:195], v[34:37]
	v_mfma_f32_16x16x32_bf16 v[34:37], v[180:183], v[196:199], v[34:37]
	v_mfma_f32_16x16x32_bf16 v[30:33], v[168:171], v[200:203], v[30:33]
	v_mfma_f32_16x16x32_bf16 v[30:33], v[172:175], v[204:207], v[30:33]
	v_mfma_f32_16x16x32_bf16 v[18:21], v[176:179], v[200:203], v[18:21]
	v_mfma_f32_16x16x32_bf16 v[18:21], v[180:183], v[204:207], v[18:21]
	v_mfma_f32_16x16x32_bf16 v[14:17], v[168:171], v[216:219], v[14:17]
	v_mfma_f32_16x16x32_bf16 v[14:17], v[172:175], v[220:223], v[14:17]
	v_mfma_f32_16x16x32_bf16 v[6:9], v[176:179], v[216:219], v[6:9]
	v_mfma_f32_16x16x32_bf16 v[6:9], v[180:183], v[220:223], v[6:9]
	s_barrier
	s_add_i32 s44, 0, 0x18000
	s_add_i32 s45, 0, 0x1c000
	s_add_u32 s16, vcc_lo, 0x80000
	s_addc_u32 s17, vcc_hi, 0
	s_mov_b32 m0, s24
	ds_read_b128 v[136:139], v143 offset:32768
	ds_read_b128 v[144:147], v143 offset:33792
	ds_read_b128 v[148:151], v143 offset:34816
	ds_read_b128 v[152:155], v143 offset:35840
	ds_read_b128 v[168:171], v143 offset:49152
	ds_read_b128 v[172:175], v143 offset:50176
	ds_read_b128 v[176:179], v143 offset:51200
	ds_read_b128 v[180:183], v143 offset:52224
	ds_read_b128 v[184:187], v142 offset:32768
	ds_read_b128 v[188:191], v142 offset:33792
	ds_read_b128 v[192:195], v142 offset:34816
	ds_read_b128 v[196:199], v142 offset:35840
	ds_read_b128 v[200:203], v142 offset:36864
	ds_read_b128 v[204:207], v142 offset:37888
	ds_read_b128 v[216:219], v142 offset:38912
	ds_read_b128 v[220:223], v142 offset:39936
	global_load_lds_dwordx4 v130, s[16:17]
	s_mov_b32 m0, s25
	s_nop 0
	global_load_lds_dwordx4 v132, s[16:17]
	s_waitcnt vmcnt(8)
	s_waitcnt lgkmcnt(0)
	s_barrier
	s_waitcnt lgkmcnt(0)
	v_mfma_f32_16x16x32_bf16 v[122:125], v[136:139], v[184:187], v[122:125]
	v_mfma_f32_16x16x32_bf16 v[122:125], v[144:147], v[188:191], v[122:125]
	v_mfma_f32_16x16x32_bf16 v[114:117], v[148:151], v[184:187], v[114:117]
	v_mfma_f32_16x16x32_bf16 v[114:117], v[152:155], v[188:191], v[114:117]
	v_mfma_f32_16x16x32_bf16 v[106:109], v[136:139], v[192:195], v[106:109]
	v_mfma_f32_16x16x32_bf16 v[106:109], v[144:147], v[196:199], v[106:109]
	v_mfma_f32_16x16x32_bf16 v[102:105], v[148:151], v[192:195], v[102:105]
	v_mfma_f32_16x16x32_bf16 v[102:105], v[152:155], v[196:199], v[102:105]
	v_mfma_f32_16x16x32_bf16 v[90:93], v[136:139], v[200:203], v[90:93]
	v_mfma_f32_16x16x32_bf16 v[90:93], v[144:147], v[204:207], v[90:93]
	v_mfma_f32_16x16x32_bf16 v[86:89], v[148:151], v[200:203], v[86:89]
	v_mfma_f32_16x16x32_bf16 v[86:89], v[152:155], v[204:207], v[86:89]
	v_mfma_f32_16x16x32_bf16 v[74:77], v[136:139], v[216:219], v[74:77]
	v_mfma_f32_16x16x32_bf16 v[74:77], v[144:147], v[220:223], v[74:77]
	v_mfma_f32_16x16x32_bf16 v[70:73], v[148:151], v[216:219], v[70:73]
	v_mfma_f32_16x16x32_bf16 v[70:73], v[152:155], v[220:223], v[70:73]
	v_mfma_f32_16x16x32_bf16 v[126:129], v[168:171], v[184:187], v[126:129]
	v_mfma_f32_16x16x32_bf16 v[126:129], v[172:175], v[188:191], v[126:129]
	v_mfma_f32_16x16x32_bf16 v[118:121], v[176:179], v[184:187], v[118:121]
	v_mfma_f32_16x16x32_bf16 v[118:121], v[180:183], v[188:191], v[118:121]
	v_mfma_f32_16x16x32_bf16 v[110:113], v[168:171], v[192:195], v[110:113]
	v_mfma_f32_16x16x32_bf16 v[110:113], v[172:175], v[196:199], v[110:113]
	v_mfma_f32_16x16x32_bf16 v[98:101], v[176:179], v[192:195], v[98:101]
	v_mfma_f32_16x16x32_bf16 v[98:101], v[180:183], v[196:199], v[98:101]
	v_mfma_f32_16x16x32_bf16 v[94:97], v[168:171], v[200:203], v[94:97]
	v_mfma_f32_16x16x32_bf16 v[94:97], v[172:175], v[204:207], v[94:97]
	v_mfma_f32_16x16x32_bf16 v[82:85], v[176:179], v[200:203], v[82:85]
	v_mfma_f32_16x16x32_bf16 v[82:85], v[180:183], v[204:207], v[82:85]
	v_mfma_f32_16x16x32_bf16 v[78:81], v[168:171], v[216:219], v[78:81]
	v_mfma_f32_16x16x32_bf16 v[78:81], v[172:175], v[220:223], v[78:81]
	v_mfma_f32_16x16x32_bf16 v[66:69], v[176:179], v[216:219], v[66:69]
	v_mfma_f32_16x16x32_bf16 v[66:69], v[180:183], v[220:223], v[66:69]
	s_barrier
	s_add_i32 s16, s44, s61
	s_mov_b32 m0, s16
	s_add_u32 s14, s14, 0x80
	s_addc_u32 s15, s15, 0
	s_add_u32 vcc_lo, vcc_lo, 0x80
	s_addc_u32 vcc_hi, vcc_hi, 0
	ds_read_b128 v[184:187], v142 offset:49152
	ds_read_b128 v[188:191], v142 offset:50176
	ds_read_b128 v[192:195], v142 offset:51200
	ds_read_b128 v[196:199], v142 offset:52224
	ds_read_b128 v[200:203], v142 offset:53248
	ds_read_b128 v[204:207], v142 offset:54272
	ds_read_b128 v[216:219], v142 offset:55296
	ds_read_b128 v[220:223], v142 offset:56320
	global_load_lds_dwordx4 v158, s[14:15]
	s_add_i32 m0, s16, 0x2000
	s_nop 0
	global_load_lds_dwordx4 v134, s[14:15]
	s_add_u32 s14, s14, 0x80000
	s_addc_u32 s15, s15, 0
	s_add_i32 s16, s45, s61
	s_mov_b32 m0, s16
	s_nop 0
	global_load_lds_dwordx4 v158, s[14:15]
	s_add_i32 m0, s16, 0x2000
	s_nop 0
	global_load_lds_dwordx4 v134, s[14:15]
	s_mov_b32 m0, s26
	s_nop 0
	global_load_lds_dwordx4 v130, vcc
	s_mov_b32 m0, s27
	s_nop 0
	global_load_lds_dwordx4 v132, vcc
	s_waitcnt vmcnt(8)
	s_waitcnt lgkmcnt(0)
	s_barrier
	s_waitcnt lgkmcnt(0)
	v_mfma_f32_16x16x32_bf16 v[58:61], v[136:139], v[184:187], v[58:61]
	v_mfma_f32_16x16x32_bf16 v[58:61], v[144:147], v[188:191], v[58:61]
	v_mfma_f32_16x16x32_bf16 v[54:57], v[148:151], v[184:187], v[54:57]
	v_mfma_f32_16x16x32_bf16 v[54:57], v[152:155], v[188:191], v[54:57]
	v_mfma_f32_16x16x32_bf16 v[42:45], v[136:139], v[192:195], v[42:45]
	v_mfma_f32_16x16x32_bf16 v[42:45], v[144:147], v[196:199], v[42:45]
	v_mfma_f32_16x16x32_bf16 v[38:41], v[148:151], v[192:195], v[38:41]
	v_mfma_f32_16x16x32_bf16 v[38:41], v[152:155], v[196:199], v[38:41]
	v_mfma_f32_16x16x32_bf16 v[26:29], v[136:139], v[200:203], v[26:29]
	v_mfma_f32_16x16x32_bf16 v[26:29], v[144:147], v[204:207], v[26:29]
	v_mfma_f32_16x16x32_bf16 v[22:25], v[148:151], v[200:203], v[22:25]
	v_mfma_f32_16x16x32_bf16 v[22:25], v[152:155], v[204:207], v[22:25]
	v_mfma_f32_16x16x32_bf16 v[10:13], v[136:139], v[216:219], v[10:13]
	v_mfma_f32_16x16x32_bf16 v[10:13], v[144:147], v[220:223], v[10:13]
	v_mfma_f32_16x16x32_bf16 v[2:5], v[148:151], v[216:219], v[2:5]
	v_mfma_f32_16x16x32_bf16 v[2:5], v[152:155], v[220:223], v[2:5]
	v_mfma_f32_16x16x32_bf16 v[62:65], v[168:171], v[184:187], v[62:65]
	v_mfma_f32_16x16x32_bf16 v[62:65], v[172:175], v[188:191], v[62:65]
	v_mfma_f32_16x16x32_bf16 v[50:53], v[176:179], v[184:187], v[50:53]
	v_mfma_f32_16x16x32_bf16 v[50:53], v[180:183], v[188:191], v[50:53]
	v_mfma_f32_16x16x32_bf16 v[46:49], v[168:171], v[192:195], v[46:49]
	v_mfma_f32_16x16x32_bf16 v[46:49], v[172:175], v[196:199], v[46:49]
	v_mfma_f32_16x16x32_bf16 v[34:37], v[176:179], v[192:195], v[34:37]
	v_mfma_f32_16x16x32_bf16 v[34:37], v[180:183], v[196:199], v[34:37]
	v_mfma_f32_16x16x32_bf16 v[30:33], v[168:171], v[200:203], v[30:33]
	v_mfma_f32_16x16x32_bf16 v[30:33], v[172:175], v[204:207], v[30:33]
	v_mfma_f32_16x16x32_bf16 v[18:21], v[176:179], v[200:203], v[18:21]
	v_mfma_f32_16x16x32_bf16 v[18:21], v[180:183], v[204:207], v[18:21]
	v_mfma_f32_16x16x32_bf16 v[14:17], v[168:171], v[216:219], v[14:17]
	v_mfma_f32_16x16x32_bf16 v[14:17], v[172:175], v[220:223], v[14:17]
	v_mfma_f32_16x16x32_bf16 v[6:9], v[176:179], v[216:219], v[6:9]
	v_mfma_f32_16x16x32_bf16 v[6:9], v[180:183], v[220:223], v[6:9]
	s_barrier
	s_cmp_gt_u32 s35, 29
	s_mov_b32 s35, s54
	s_cbranch_scc1 .LBB0_279

.Lsp_LBB0353:
	s_add_u32 s36, s0, 0x100
	s_addc_u32 s37, s1, 0
	s_add_i32 s27, 0, 0x10000
	s_cmpk_eq_i32 s26, 0x52
	s_cselect_b32 s69, s65, s37
	s_cselect_b32 s68, s64, s36
	v_add_u32_e32 v144, s27, v146
	s_cselect_b32 s15, s67, s25
	s_cselect_b32 s14, s66, s24
	s_add_i32 s28, 0, 0x14000
	ds_read_b128 v[140:143], v144
	ds_read_b128 v[150:153], v144 offset:1024
	ds_read_b128 v[154:157], v144 offset:2048
	ds_read_b128 v[168:171], v144 offset:3072
	ds_read_b128 v[172:175], v144 offset:16384
	ds_read_b128 v[176:179], v144 offset:17408
	ds_read_b128 v[180:183], v144 offset:18432
	ds_read_b128 v[184:187], v144 offset:19456
	s_add_i32 m0, s59, 0xc000
	ds_read_b128 v[188:191], v148
	ds_read_b128 v[192:195], v148 offset:1024
	ds_read_b128 v[196:199], v148 offset:2048
	ds_read_b128 v[200:203], v148 offset:3072
	ds_read_b128 v[204:207], v148 offset:4096
	ds_read_b128 v[216:219], v148 offset:5120
	ds_read_b128 v[220:223], v148 offset:6144
	ds_read_b128 v[224:227], v148 offset:7168
	global_load_lds_dwordx4 v136, s[0:1]
	s_add_i32 m0, s59, 0xe000
	s_nop 0
	global_load_lds_dwordx4 v138, s[0:1]
	s_waitcnt vmcnt(8)
	s_waitcnt lgkmcnt(0)
	s_barrier
	s_waitcnt lgkmcnt(0)
	v_mfma_f32_16x16x32_bf16 v[126:129], v[140:143], v[188:191], v[126:129]
	v_mfma_f32_16x16x32_bf16 v[126:129], v[150:153], v[192:195], v[126:129]
	v_mfma_f32_16x16x32_bf16 v[122:125], v[154:157], v[188:191], v[122:125]
	v_mfma_f32_16x16x32_bf16 v[122:125], v[168:171], v[192:195], v[122:125]
	v_mfma_f32_16x16x32_bf16 v[110:113], v[140:143], v[196:199], v[110:113]
	v_mfma_f32_16x16x32_bf16 v[110:113], v[150:153], v[200:203], v[110:113]
	v_mfma_f32_16x16x32_bf16 v[106:109], v[154:157], v[196:199], v[106:109]
	v_mfma_f32_16x16x32_bf16 v[106:109], v[168:171], v[200:203], v[106:109]
	v_mfma_f32_16x16x32_bf16 v[94:97], v[140:143], v[204:207], v[94:97]
	v_mfma_f32_16x16x32_bf16 v[94:97], v[150:153], v[216:219], v[94:97]
	v_mfma_f32_16x16x32_bf16 v[90:93], v[154:157], v[204:207], v[90:93]
	v_mfma_f32_16x16x32_bf16 v[90:93], v[168:171], v[216:219], v[90:93]
	v_mfma_f32_16x16x32_bf16 v[78:81], v[140:143], v[220:223], v[78:81]
	v_mfma_f32_16x16x32_bf16 v[78:81], v[150:153], v[224:227], v[78:81]
	v_mfma_f32_16x16x32_bf16 v[74:77], v[154:157], v[220:223], v[74:77]
	v_mfma_f32_16x16x32_bf16 v[74:77], v[168:171], v[224:227], v[74:77]
	v_mfma_f32_16x16x32_bf16 v[118:121], v[172:175], v[188:191], v[118:121]
	v_mfma_f32_16x16x32_bf16 v[118:121], v[176:179], v[192:195], v[118:121]
	v_mfma_f32_16x16x32_bf16 v[114:117], v[180:183], v[188:191], v[114:117]
	v_mfma_f32_16x16x32_bf16 v[114:117], v[184:187], v[192:195], v[114:117]
	v_mfma_f32_16x16x32_bf16 v[102:105], v[172:175], v[196:199], v[102:105]
	v_mfma_f32_16x16x32_bf16 v[102:105], v[176:179], v[200:203], v[102:105]
	v_mfma_f32_16x16x32_bf16 v[98:101], v[180:183], v[196:199], v[98:101]
	v_mfma_f32_16x16x32_bf16 v[98:101], v[184:187], v[200:203], v[98:101]
	v_mfma_f32_16x16x32_bf16 v[86:89], v[172:175], v[204:207], v[86:89]
	v_mfma_f32_16x16x32_bf16 v[86:89], v[176:179], v[216:219], v[86:89]
	v_mfma_f32_16x16x32_bf16 v[82:85], v[180:183], v[204:207], v[82:85]
	v_mfma_f32_16x16x32_bf16 v[82:85], v[184:187], v[216:219], v[82:85]
	v_mfma_f32_16x16x32_bf16 v[70:73], v[172:175], v[220:223], v[70:73]
	v_mfma_f32_16x16x32_bf16 v[70:73], v[176:179], v[224:227], v[70:73]
	v_mfma_f32_16x16x32_bf16 v[66:69], v[180:183], v[220:223], v[66:69]
	v_mfma_f32_16x16x32_bf16 v[66:69], v[184:187], v[224:227], v[66:69]
	s_barrier
	s_add_i32 s0, s27, s58
	s_mov_b32 m0, s0
	ds_read_b128 v[188:191], v148 offset:16384
	ds_read_b128 v[192:195], v148 offset:17408
	ds_read_b128 v[196:199], v148 offset:18432
	ds_read_b128 v[200:203], v148 offset:19456
	ds_read_b128 v[204:207], v148 offset:20480
	ds_read_b128 v[216:219], v148 offset:21504
	ds_read_b128 v[220:223], v148 offset:22528
	ds_read_b128 v[224:227], v148 offset:23552
	global_load_lds_dwordx4 v158, s[14:15]
	s_add_i32 m0, s0, 0x2000
	s_add_u32 s0, s14, 0x158000
	s_addc_u32 s1, s15, 0
	s_add_i32 s27, s28, s58
	global_load_lds_dwordx4 v134, s[14:15]
	s_mov_b32 m0, s27
	s_nop 0
	global_load_lds_dwordx4 v158, s[0:1]
	s_add_i32 m0, s27, 0x2000
	s_nop 0
	global_load_lds_dwordx4 v134, s[0:1]
	s_mov_b32 m0, s59
	s_nop 0
	global_load_lds_dwordx4 v130, s[68:69]
	s_mov_b32 m0, s70
	s_nop 0
	global_load_lds_dwordx4 v132, s[68:69]
	s_waitcnt vmcnt(8)
	s_waitcnt lgkmcnt(0)
	s_barrier
	s_waitcnt lgkmcnt(0)
	v_mfma_f32_16x16x32_bf16 v[62:65], v[140:143], v[188:191], v[62:65]
	v_mfma_f32_16x16x32_bf16 v[62:65], v[150:153], v[192:195], v[62:65]
	v_mfma_f32_16x16x32_bf16 v[58:61], v[154:157], v[188:191], v[58:61]
	v_mfma_f32_16x16x32_bf16 v[58:61], v[168:171], v[192:195], v[58:61]
	v_mfma_f32_16x16x32_bf16 v[46:49], v[140:143], v[196:199], v[46:49]
	v_mfma_f32_16x16x32_bf16 v[46:49], v[150:153], v[200:203], v[46:49]
	v_mfma_f32_16x16x32_bf16 v[42:45], v[154:157], v[196:199], v[42:45]
	v_mfma_f32_16x16x32_bf16 v[42:45], v[168:171], v[200:203], v[42:45]
	v_mfma_f32_16x16x32_bf16 v[30:33], v[140:143], v[204:207], v[30:33]
	v_mfma_f32_16x16x32_bf16 v[30:33], v[150:153], v[216:219], v[30:33]
	v_mfma_f32_16x16x32_bf16 v[26:29], v[154:157], v[204:207], v[26:29]
	v_mfma_f32_16x16x32_bf16 v[26:29], v[168:171], v[216:219], v[26:29]
	v_mfma_f32_16x16x32_bf16 v[14:17], v[140:143], v[220:223], v[14:17]
	v_mfma_f32_16x16x32_bf16 v[14:17], v[150:153], v[224:227], v[14:17]
	v_mfma_f32_16x16x32_bf16 v[10:13], v[154:157], v[220:223], v[10:13]
	v_mfma_f32_16x16x32_bf16 v[10:13], v[168:171], v[224:227], v[10:13]
	v_mfma_f32_16x16x32_bf16 v[54:57], v[172:175], v[188:191], v[54:57]
	v_mfma_f32_16x16x32_bf16 v[54:57], v[176:179], v[192:195], v[54:57]
	v_mfma_f32_16x16x32_bf16 v[50:53], v[180:183], v[188:191], v[50:53]
	v_mfma_f32_16x16x32_bf16 v[50:53], v[184:187], v[192:195], v[50:53]
	v_mfma_f32_16x16x32_bf16 v[38:41], v[172:175], v[196:199], v[38:41]
	v_mfma_f32_16x16x32_bf16 v[38:41], v[176:179], v[200:203], v[38:41]
	v_mfma_f32_16x16x32_bf16 v[34:37], v[180:183], v[196:199], v[34:37]
	v_mfma_f32_16x16x32_bf16 v[34:37], v[184:187], v[200:203], v[34:37]
	v_mfma_f32_16x16x32_bf16 v[22:25], v[172:175], v[204:207], v[22:25]
	v_mfma_f32_16x16x32_bf16 v[22:25], v[176:179], v[216:219], v[22:25]
	v_mfma_f32_16x16x32_bf16 v[18:21], v[180:183], v[204:207], v[18:21]
	v_mfma_f32_16x16x32_bf16 v[18:21], v[184:187], v[216:219], v[18:21]
	v_mfma_f32_16x16x32_bf16 v[6:9], v[172:175], v[220:223], v[6:9]
	v_mfma_f32_16x16x32_bf16 v[6:9], v[176:179], v[224:227], v[6:9]
	v_mfma_f32_16x16x32_bf16 v[2:5], v[180:183], v[220:223], v[2:5]
	v_mfma_f32_16x16x32_bf16 v[2:5], v[184:187], v[224:227], v[2:5]
	s_barrier
	s_add_i32 s27, 0, 0x18000
	s_add_i32 s28, 0, 0x1c000
	ds_read_b128 v[140:143], v144 offset:32768
	ds_read_b128 v[150:153], v144 offset:33792
	ds_read_b128 v[154:157], v144 offset:34816
	ds_read_b128 v[168:171], v144 offset:35840
	ds_read_b128 v[172:175], v144 offset:49152
	ds_read_b128 v[176:179], v144 offset:50176
	ds_read_b128 v[180:183], v144 offset:51200
	ds_read_b128 v[184:187], v144 offset:52224
	s_add_u32 s0, s68, 0x158000
	s_addc_u32 s1, s69, 0
	s_mov_b32 m0, s71
	ds_read_b128 v[188:191], v148 offset:32768
	ds_read_b128 v[192:195], v148 offset:33792
	ds_read_b128 v[196:199], v148 offset:34816
	ds_read_b128 v[200:203], v148 offset:35840
	ds_read_b128 v[204:207], v148 offset:36864
	ds_read_b128 v[216:219], v148 offset:37888
	ds_read_b128 v[220:223], v148 offset:38912
	ds_read_b128 v[224:227], v148 offset:39936
	global_load_lds_dwordx4 v130, s[0:1]
	s_mov_b32 m0, s72
	s_nop 0
	global_load_lds_dwordx4 v132, s[0:1]
	s_waitcnt vmcnt(8)
	s_waitcnt lgkmcnt(0)
	s_barrier
	s_waitcnt lgkmcnt(0)
	v_mfma_f32_16x16x32_bf16 v[126:129], v[140:143], v[188:191], v[126:129]
	v_mfma_f32_16x16x32_bf16 v[126:129], v[150:153], v[192:195], v[126:129]
	v_mfma_f32_16x16x32_bf16 v[122:125], v[154:157], v[188:191], v[122:125]
	v_mfma_f32_16x16x32_bf16 v[122:125], v[168:171], v[192:195], v[122:125]
	v_mfma_f32_16x16x32_bf16 v[110:113], v[140:143], v[196:199], v[110:113]
	v_mfma_f32_16x16x32_bf16 v[110:113], v[150:153], v[200:203], v[110:113]
	v_mfma_f32_16x16x32_bf16 v[106:109], v[154:157], v[196:199], v[106:109]
	v_mfma_f32_16x16x32_bf16 v[106:109], v[168:171], v[200:203], v[106:109]
	v_mfma_f32_16x16x32_bf16 v[94:97], v[140:143], v[204:207], v[94:97]
	v_mfma_f32_16x16x32_bf16 v[94:97], v[150:153], v[216:219], v[94:97]
	v_mfma_f32_16x16x32_bf16 v[90:93], v[154:157], v[204:207], v[90:93]
	v_mfma_f32_16x16x32_bf16 v[90:93], v[168:171], v[216:219], v[90:93]
	v_mfma_f32_16x16x32_bf16 v[78:81], v[140:143], v[220:223], v[78:81]
	v_mfma_f32_16x16x32_bf16 v[78:81], v[150:153], v[224:227], v[78:81]
	v_mfma_f32_16x16x32_bf16 v[74:77], v[154:157], v[220:223], v[74:77]
	v_mfma_f32_16x16x32_bf16 v[74:77], v[168:171], v[224:227], v[74:77]
	v_mfma_f32_16x16x32_bf16 v[118:121], v[172:175], v[188:191], v[118:121]
	v_mfma_f32_16x16x32_bf16 v[118:121], v[176:179], v[192:195], v[118:121]
	v_mfma_f32_16x16x32_bf16 v[114:117], v[180:183], v[188:191], v[114:117]
	v_mfma_f32_16x16x32_bf16 v[114:117], v[184:187], v[192:195], v[114:117]
	v_mfma_f32_16x16x32_bf16 v[102:105], v[172:175], v[196:199], v[102:105]
	v_mfma_f32_16x16x32_bf16 v[102:105], v[176:179], v[200:203], v[102:105]
	v_mfma_f32_16x16x32_bf16 v[98:101], v[180:183], v[196:199], v[98:101]
	v_mfma_f32_16x16x32_bf16 v[98:101], v[184:187], v[200:203], v[98:101]
	v_mfma_f32_16x16x32_bf16 v[86:89], v[172:175], v[204:207], v[86:89]
	v_mfma_f32_16x16x32_bf16 v[86:89], v[176:179], v[216:219], v[86:89]
	v_mfma_f32_16x16x32_bf16 v[82:85], v[180:183], v[204:207], v[82:85]
	v_mfma_f32_16x16x32_bf16 v[82:85], v[184:187], v[216:219], v[82:85]
	v_mfma_f32_16x16x32_bf16 v[70:73], v[172:175], v[220:223], v[70:73]
	v_mfma_f32_16x16x32_bf16 v[70:73], v[176:179], v[224:227], v[70:73]
	v_mfma_f32_16x16x32_bf16 v[66:69], v[180:183], v[220:223], v[66:69]
	v_mfma_f32_16x16x32_bf16 v[66:69], v[184:187], v[224:227], v[66:69]
	s_barrier
	s_add_i32 s0, s27, s58
	s_add_u32 s100, s14, 0x80
	s_addc_u32 s101, s15, 0
	s_mov_b32 m0, s0
	ds_read_b128 v[188:191], v148 offset:49152
	ds_read_b128 v[192:195], v148 offset:50176
	ds_read_b128 v[196:199], v148 offset:51200
	ds_read_b128 v[200:203], v148 offset:52224
	ds_read_b128 v[204:207], v148 offset:53248
	ds_read_b128 v[216:219], v148 offset:54272
	ds_read_b128 v[220:223], v148 offset:55296
	ds_read_b128 v[224:227], v148 offset:56320
	global_load_lds_dwordx4 v158, s[100:101]
	s_add_i32 m0, s0, 0x2000
	s_add_u32 s0, s14, 0x158080
	s_addc_u32 s1, s15, 0
	s_add_i32 s14, s28, s58
	global_load_lds_dwordx4 v134, s[100:101]
	s_add_u32 s100, s68, 0x80
	s_addc_u32 s101, s69, 0
	s_mov_b32 m0, s14
	s_nop 0
	global_load_lds_dwordx4 v158, s[0:1]
	s_add_i32 m0, s14, 0x2000
	s_nop 0
	global_load_lds_dwordx4 v134, s[0:1]
	s_mov_b32 m0, s73
	s_nop 0
	global_load_lds_dwordx4 v130, s[100:101]
	s_mov_b32 m0, s74
	s_nop 0
	global_load_lds_dwordx4 v132, s[100:101]
	s_waitcnt vmcnt(8)
	s_waitcnt lgkmcnt(0)
	s_barrier
	s_waitcnt lgkmcnt(0)
	v_mfma_f32_16x16x32_bf16 v[62:65], v[140:143], v[188:191], v[62:65]
	v_mfma_f32_16x16x32_bf16 v[62:65], v[150:153], v[192:195], v[62:65]
	v_mfma_f32_16x16x32_bf16 v[58:61], v[154:157], v[188:191], v[58:61]
	v_mfma_f32_16x16x32_bf16 v[58:61], v[168:171], v[192:195], v[58:61]
	v_mfma_f32_16x16x32_bf16 v[46:49], v[140:143], v[196:199], v[46:49]
	v_mfma_f32_16x16x32_bf16 v[46:49], v[150:153], v[200:203], v[46:49]
	v_mfma_f32_16x16x32_bf16 v[42:45], v[154:157], v[196:199], v[42:45]
	v_mfma_f32_16x16x32_bf16 v[42:45], v[168:171], v[200:203], v[42:45]
	v_mfma_f32_16x16x32_bf16 v[30:33], v[140:143], v[204:207], v[30:33]
	v_mfma_f32_16x16x32_bf16 v[30:33], v[150:153], v[216:219], v[30:33]
	v_mfma_f32_16x16x32_bf16 v[26:29], v[154:157], v[204:207], v[26:29]
	v_mfma_f32_16x16x32_bf16 v[26:29], v[168:171], v[216:219], v[26:29]
	v_mfma_f32_16x16x32_bf16 v[14:17], v[140:143], v[220:223], v[14:17]
	v_mfma_f32_16x16x32_bf16 v[14:17], v[150:153], v[224:227], v[14:17]
	v_mfma_f32_16x16x32_bf16 v[10:13], v[154:157], v[220:223], v[10:13]
	v_mfma_f32_16x16x32_bf16 v[10:13], v[168:171], v[224:227], v[10:13]
	v_mfma_f32_16x16x32_bf16 v[54:57], v[172:175], v[188:191], v[54:57]
	v_mfma_f32_16x16x32_bf16 v[54:57], v[176:179], v[192:195], v[54:57]
	v_mfma_f32_16x16x32_bf16 v[50:53], v[180:183], v[188:191], v[50:53]
	v_mfma_f32_16x16x32_bf16 v[50:53], v[184:187], v[192:195], v[50:53]
	v_mfma_f32_16x16x32_bf16 v[38:41], v[172:175], v[196:199], v[38:41]
	v_mfma_f32_16x16x32_bf16 v[38:41], v[176:179], v[200:203], v[38:41]
	v_mfma_f32_16x16x32_bf16 v[34:37], v[180:183], v[196:199], v[34:37]
	v_mfma_f32_16x16x32_bf16 v[34:37], v[184:187], v[200:203], v[34:37]
	v_mfma_f32_16x16x32_bf16 v[22:25], v[172:175], v[204:207], v[22:25]
	v_mfma_f32_16x16x32_bf16 v[22:25], v[176:179], v[216:219], v[22:25]
	v_mfma_f32_16x16x32_bf16 v[18:21], v[180:183], v[204:207], v[18:21]
	v_mfma_f32_16x16x32_bf16 v[18:21], v[184:187], v[216:219], v[18:21]
	v_mfma_f32_16x16x32_bf16 v[6:9], v[172:175], v[220:223], v[6:9]
	v_mfma_f32_16x16x32_bf16 v[6:9], v[176:179], v[224:227], v[6:9]
	v_mfma_f32_16x16x32_bf16 v[2:5], v[180:183], v[220:223], v[2:5]
	v_mfma_f32_16x16x32_bf16 v[2:5], v[184:187], v[224:227], v[2:5]
	s_barrier
	s_add_i32 s26, s26, 2
	s_add_u32 s24, s24, 0x100
	s_addc_u32 s25, s25, 0
	s_cmpk_gt_u32 s26, 0x53
	s_mov_b64 s[0:1], s[36:37]
	s_cbranch_scc0 .LBB0_353
	s_and_b64 vcc, exec, s[12:13]
	s_cbranch_vccz .LBB0_356
	s_barrier
